# wave_sum in the ERES0/ERES1/PRO row loops: xor-32/16 via v_permlane32/16_swap, xor-8/4/2/1 via row_ror / quad_perm DPP adds (were six dependent ds_bpermute round trips per sum); same pairing, identica
# baseline (speedup 1.0000x reference)
.LBB0_119:
	s_or_b64 exec, exec, s[44:45]
	v_ashrrev_i32_e32 v19, 31, v18
	v_lshlrev_b64 v[18:19], 11, v[18:19]
	v_lshl_add_u64 v[20:21], v[60:61], 0, v[18:19]
	v_lshl_add_u64 v[18:19], v[62:63], 0, v[18:19]
	global_load_dwordx4 v[30:33], v[20:21], off
	global_load_dwordx4 v[26:29], v[18:19], off
	global_load_dwordx4 v[22:25], v[20:21], off offset:1024
	s_nop 0
	global_load_dwordx4 v[18:21], v[18:19], off offset:1024
	s_waitcnt vmcnt(8)
	v_mov_b32_e32 v51, v50
	s_nop 1
	v_permlane32_swap_b32_e32 v50, v51
	s_waitcnt lgkmcnt(0)
	v_add_f32_e32 v50, v50, v51
	v_mov_b32_e32 v51, v50
	s_nop 1
	v_permlane16_swap_b32_e32 v50, v51
	s_waitcnt lgkmcnt(0)
	v_add_f32_e32 v50, v50, v51
	s_nop 1
	v_add_f32_dpp v51, v50, v50 row_ror:8 row_mask:0xf bank_mask:0xf
	s_waitcnt lgkmcnt(0)
	v_mov_b32_e32 v50, v51
	s_nop 1
	v_add_f32_dpp v51, v50, v50 row_ror:4 row_mask:0xf bank_mask:0xf
	s_waitcnt lgkmcnt(0)
	v_mov_b32_e32 v50, v51
	s_nop 1
	v_add_f32_dpp v51, v50, v50 quad_perm:[2,3,0,1] row_mask:0xf bank_mask:0xf
	s_waitcnt lgkmcnt(0)
	v_mov_b32_e32 v50, v51
	s_nop 1
	v_add_f32_dpp v51, v50, v50 quad_perm:[1,0,3,2] row_mask:0xf bank_mask:0xf
	s_waitcnt lgkmcnt(0)
	v_mov_b32_e32 v50, v51
	v_fmamk_f32 v50, v50, 0x3a800000, v229
	v_cmp_gt_f32_e32 vcc, s5, v50
	v_mul_f32_e32 v51, 0x4f800000, v50
	s_nop 0
	v_cndmask_b32_e32 v50, v50, v51, vcc
	v_sqrt_f32_e32 v51, v50
	s_nop 0
	v_add_u32_e32 v52, -1, v51
	v_fma_f32 v53, -v52, v51, v50
	v_cmp_ge_f32_e64 s[44:45], 0, v53
	v_add_u32_e32 v53, 1, v51
	s_nop 0
	v_cndmask_b32_e64 v52, v51, v52, s[44:45]
	v_fma_f32 v51, -v53, v51, v50
	v_cmp_lt_f32_e64 s[44:45], 0, v51
	s_nop 1
	v_cndmask_b32_e64 v51, v52, v53, s[44:45]
	v_mul_f32_e32 v52, 0x37800000, v51
	v_cndmask_b32_e32 v51, v51, v52, vcc
	v_cmp_class_f32_e32 vcc, v50, v230
	s_mov_b64 s[44:45], -1
	s_nop 0
	v_cndmask_b32_e32 v50, v51, v50, vcc
	v_div_scale_f32 v51, s[18:19], v50, v50, 1.0
	v_rcp_f32_e32 v52, v51
	s_nop 0
	v_fma_f32 v53, -v51, v52, 1.0
	v_fmac_f32_e32 v52, v53, v52
	v_div_scale_f32 v53, vcc, 1.0, v50, 1.0
	v_mul_f32_e32 v70, v53, v52
	v_fma_f32 v71, -v51, v70, v53
	v_fmac_f32_e32 v70, v71, v52
	v_fma_f32 v51, -v51, v70, v53
	v_div_fmas_f32 v51, v51, v52, v70
	v_div_fixup_f32 v70, v51, v50, 1.0
	s_waitcnt vmcnt(5)
	v_lshlrev_b32_e32 v52, 16, v42
	v_and_b32_e32 v53, 0xffff0000, v42
	v_lshlrev_b32_e32 v42, 16, v43
	v_and_b32_e32 v43, 0xffff0000, v43
	v_lshlrev_b32_e32 v50, 16, v46
	v_and_b32_e32 v51, 0xffff0000, v46
	v_pk_mul_f32 v[52:53], v[70:71], v[52:53] op_sel_hi:[0,1]
	v_lshlrev_b32_e32 v46, 16, v47
	v_and_b32_e32 v47, 0xffff0000, v47
	v_pk_mul_f32 v[42:43], v[70:71], v[42:43] op_sel_hi:[0,1]
	v_pk_fma_f32 v[50:51], v[6:7], v[52:53], v[50:51]
	v_pk_fma_f32 v[52:53], v[8:9], v[42:43], v[46:47]
	v_lshlrev_b32_e32 v46, 16, v44
	v_and_b32_e32 v47, 0xffff0000, v44
	v_lshlrev_b32_e32 v42, 16, v48
	v_and_b32_e32 v43, 0xffff0000, v48
	v_pk_mul_f32 v[46:47], v[70:71], v[46:47] op_sel_hi:[0,1]
	v_lshlrev_b32_e32 v44, 16, v45
	v_and_b32_e32 v45, 0xffff0000, v45
	v_pk_fma_f32 v[42:43], v[14:15], v[46:47], v[42:43]
	v_lshlrev_b32_e32 v46, 16, v49
	v_and_b32_e32 v47, 0xffff0000, v49
	v_pk_mul_f32 v[44:45], v[70:71], v[44:45] op_sel_hi:[0,1]
	v_pk_fma_f32 v[44:45], v[16:17], v[44:45], v[46:47]
	s_and_b64 vcc, exec, s[26:27]
	s_cbranch_vccz .LBB0_121
	v_cvt_pk_bf16_f32 v46, v50, v51
	v_cvt_pk_bf16_f32 v47, v52, v53
	v_cvt_pk_bf16_f32 v48, v42, v43
	v_cvt_pk_bf16_f32 v49, v44, v45
	global_store_dwordx4 v[68:69], v[46:49], off
	v_lshlrev_b32_e32 v79, 16, v47
	v_lshlrev_b32_e32 v78, 16, v46
	v_and_b32_e32 v47, 0xffff0000, v47
	v_and_b32_e32 v46, 0xffff0000, v46
	v_pk_mul_f32 v[46:47], v[46:47], v[46:47]
	s_mov_b64 s[44:45], 0
	v_pk_fma_f32 v[46:47], v[78:79], v[78:79], v[46:47]
	v_lshlrev_b32_e32 v79, 16, v49
	v_lshlrev_b32_e32 v78, 16, v48
	v_and_b32_e32 v49, 0xffff0000, v49
	v_and_b32_e32 v48, 0xffff0000, v48
	v_pk_mul_f32 v[48:49], v[48:49], v[48:49]
	v_add_f32_e32 v46, v46, v47
	v_pk_fma_f32 v[48:49], v[78:79], v[78:79], v[48:49]
	s_nop 0
	v_add_f32_e32 v46, v46, v48
	v_add_f32_e32 v48, v46, v49

.LBB0_129:
	v_mov_b32_e32 v34, v38
	s_nop 1
	v_permlane32_swap_b32_e32 v38, v34
	s_waitcnt lgkmcnt(0)
	v_add_f32_e32 v34, v38, v34
	v_mov_b32_e32 v35, v34
	s_nop 1
	v_permlane16_swap_b32_e32 v34, v35
	s_waitcnt lgkmcnt(0)
	v_add_f32_e32 v34, v34, v35
	s_nop 1
	v_add_f32_dpp v35, v34, v34 row_ror:8 row_mask:0xf bank_mask:0xf
	s_waitcnt lgkmcnt(0)
	v_mov_b32_e32 v34, v35
	s_nop 1
	v_add_f32_dpp v35, v34, v34 row_ror:4 row_mask:0xf bank_mask:0xf
	s_waitcnt lgkmcnt(0)
	v_mov_b32_e32 v34, v35
	s_nop 1
	v_add_f32_dpp v35, v34, v34 quad_perm:[2,3,0,1] row_mask:0xf bank_mask:0xf
	s_waitcnt lgkmcnt(0)
	v_mov_b32_e32 v34, v35
	s_nop 1
	v_add_f32_dpp v35, v34, v34 quad_perm:[1,0,3,2] row_mask:0xf bank_mask:0xf
	s_and_saveexec_b64 s[78:79], s[42:43]
	s_cbranch_execz .LBB0_131
	s_waitcnt lgkmcnt(0)
	v_mov_b32_e32 v34, v35
	v_fmamk_f32 v34, v34, 0x3a800000, v229
	v_mul_f32_e32 v35, 0x4f800000, v34
	v_cmp_gt_f32_e32 vcc, s5, v34
	s_nop 1
	v_cndmask_b32_e32 v34, v34, v35, vcc
	v_sqrt_f32_e32 v35, v34
	s_nop 0
	v_add_u32_e32 v36, -1, v35
	v_fma_f32 v38, -v36, v35, v34
	v_add_u32_e32 v37, 1, v35
	v_cmp_ge_f32_e64 s[50:51], 0, v38
	s_nop 1
	v_cndmask_b32_e64 v36, v35, v36, s[50:51]
	v_fma_f32 v35, -v37, v35, v34
	v_cmp_lt_f32_e64 s[50:51], 0, v35
	s_nop 1
	v_cndmask_b32_e64 v35, v36, v37, s[50:51]
	v_mul_f32_e32 v36, 0x37800000, v35
	v_cndmask_b32_e32 v35, v35, v36, vcc
	v_cmp_class_f32_e32 vcc, v34, v230
	s_nop 1
	v_cndmask_b32_e32 v34, v35, v34, vcc
	v_div_scale_f32 v35, s[18:19], v34, v34, 1.0
	v_rcp_f32_e32 v36, v35
	s_nop 0
	v_fma_f32 v37, -v35, v36, 1.0
	v_fmac_f32_e32 v36, v37, v36
	v_div_scale_f32 v37, vcc, 1.0, v34, 1.0
	v_mul_f32_e32 v38, v37, v36
	v_fma_f32 v39, -v35, v38, v37
	v_fmac_f32_e32 v38, v39, v36
	v_fma_f32 v35, -v35, v38, v37
	v_div_fmas_f32 v35, v35, v36, v38
	v_div_fixup_f32 v36, v35, v34, 1.0
	v_lshl_add_u64 v[34:35], v[66:67], 2, s[86:87]
	global_store_dword v[34:35], v36, off

.LBB0_132:
	v_mov_b32_e32 v34, v65
	s_nop 1
	v_permlane32_swap_b32_e32 v65, v34
	s_waitcnt lgkmcnt(0)
	v_add_f32_e32 v34, v65, v34
	v_mov_b32_e32 v35, v34
	s_nop 1
	v_permlane16_swap_b32_e32 v34, v35
	v_ashrrev_i32_e32 v65, 31, v64
	s_waitcnt lgkmcnt(0)
	v_add_f32_e32 v34, v34, v35
	s_nop 1
	v_add_f32_dpp v35, v34, v34 row_ror:8 row_mask:0xf bank_mask:0xf
	s_waitcnt lgkmcnt(0)
	v_mov_b32_e32 v34, v35
	s_nop 1
	v_add_f32_dpp v35, v34, v34 row_ror:4 row_mask:0xf bank_mask:0xf
	s_waitcnt lgkmcnt(0)
	v_mov_b32_e32 v34, v35
	s_nop 1
	v_add_f32_dpp v35, v34, v34 quad_perm:[2,3,0,1] row_mask:0xf bank_mask:0xf
	s_waitcnt lgkmcnt(0)
	v_mov_b32_e32 v34, v35
	s_nop 1
	v_add_f32_dpp v35, v34, v34 quad_perm:[1,0,3,2] row_mask:0xf bank_mask:0xf
	s_waitcnt lgkmcnt(0)
	v_mov_b32_e32 v34, v35
	v_fmamk_f32 v34, v34, 0x3a800000, v229
	v_cmp_gt_f32_e32 vcc, s5, v34
	v_mul_f32_e32 v35, 0x4f800000, v34
	s_nop 0
	v_cndmask_b32_e32 v34, v34, v35, vcc
	v_sqrt_f32_e32 v35, v34
	s_nop 0
	v_add_u32_e32 v36, -1, v35
	v_fma_f32 v37, -v36, v35, v34
	v_cmp_ge_f32_e64 s[46:47], 0, v37
	v_add_u32_e32 v37, 1, v35
	s_nop 0
	v_cndmask_b32_e64 v36, v35, v36, s[46:47]
	v_fma_f32 v35, -v37, v35, v34
	v_cmp_lt_f32_e64 s[46:47], 0, v35
	s_nop 1
	v_cndmask_b32_e64 v35, v36, v37, s[46:47]
	v_mul_f32_e32 v36, 0x37800000, v35
	v_cndmask_b32_e32 v35, v35, v36, vcc
	v_cmp_class_f32_e32 vcc, v34, v230
	s_mov_b64 s[46:47], -1
	s_nop 0
	v_cndmask_b32_e32 v34, v35, v34, vcc
	v_div_scale_f32 v35, s[18:19], v34, v34, 1.0
	v_rcp_f32_e32 v36, v35
	s_nop 0
	v_fma_f32 v37, -v35, v36, 1.0
	v_fmac_f32_e32 v36, v37, v36
	v_div_scale_f32 v37, vcc, 1.0, v34, 1.0
	v_mul_f32_e32 v38, v37, v36
	v_fma_f32 v39, -v35, v38, v37
	v_fmac_f32_e32 v38, v39, v36
	v_fma_f32 v35, -v35, v38, v37
	v_div_fmas_f32 v35, v35, v36, v38
	v_div_fixup_f32 v38, v35, v34, 1.0
	v_lshlrev_b64 v[34:35], 11, v[64:65]
	s_waitcnt vmcnt(2)
	v_lshlrev_b32_e32 v36, 16, v26
	v_and_b32_e32 v37, 0xffff0000, v26
	v_lshlrev_b32_e32 v26, 16, v27
	v_and_b32_e32 v27, 0xffff0000, v27
	v_lshl_add_u64 v[40:41], s[36:37], 0, v[34:35]
	v_lshlrev_b32_e32 v34, 16, v30
	v_and_b32_e32 v35, 0xffff0000, v30
	v_pk_mul_f32 v[36:37], v[38:39], v[36:37] op_sel_hi:[0,1]
	v_lshlrev_b32_e32 v30, 16, v31
	v_and_b32_e32 v31, 0xffff0000, v31
	v_pk_mul_f32 v[26:27], v[38:39], v[26:27] op_sel_hi:[0,1]
	v_pk_fma_f32 v[34:35], v[6:7], v[36:37], v[34:35]
	v_pk_fma_f32 v[36:37], v[8:9], v[26:27], v[30:31]
	v_lshlrev_b32_e32 v30, 16, v28
	v_and_b32_e32 v31, 0xffff0000, v28
	v_lshlrev_b32_e32 v26, 16, v32
	v_and_b32_e32 v27, 0xffff0000, v32
	v_pk_mul_f32 v[30:31], v[38:39], v[30:31] op_sel_hi:[0,1]
	v_lshlrev_b32_e32 v28, 16, v29
	v_and_b32_e32 v29, 0xffff0000, v29
	v_pk_fma_f32 v[26:27], v[14:15], v[30:31], v[26:27]
	v_lshlrev_b32_e32 v30, 16, v33
	v_and_b32_e32 v31, 0xffff0000, v33
	v_pk_mul_f32 v[28:29], v[38:39], v[28:29] op_sel_hi:[0,1]
	v_pk_fma_f32 v[28:29], v[16:17], v[28:29], v[30:31]
	s_and_b64 vcc, exec, s[44:45]
	v_lshlrev_b32_e32 v30, 1, v54
	s_cbranch_vccnz .LBB0_134
	v_mov_b32_e32 v31, v1
	v_cvt_pk_bf16_f32 v42, v34, v35
	v_cvt_pk_bf16_f32 v43, v36, v37
	v_lshl_add_u64 v[32:33], v[40:41], 0, v[30:31]
	v_cvt_pk_bf16_f32 v44, v26, v27
	v_cvt_pk_bf16_f32 v45, v28, v29
	global_store_dwordx4 v[32:33], v[42:45], off
	v_lshlrev_b32_e32 v33, 16, v43
	v_lshlrev_b32_e32 v32, 16, v42
	v_and_b32_e32 v43, 0xffff0000, v43
	v_and_b32_e32 v42, 0xffff0000, v42
	v_pk_mul_f32 v[42:43], v[42:43], v[42:43]
	s_mov_b64 s[46:47], 0
	v_pk_fma_f32 v[32:33], v[32:33], v[32:33], v[42:43]
	v_lshlrev_b32_e32 v43, 16, v45
	v_lshlrev_b32_e32 v42, 16, v44
	v_and_b32_e32 v45, 0xffff0000, v45
	v_and_b32_e32 v44, 0xffff0000, v44
	v_pk_mul_f32 v[44:45], v[44:45], v[44:45]
	v_add_f32_e32 v31, v32, v33
	v_pk_fma_f32 v[42:43], v[42:43], v[42:43], v[44:45]
	s_nop 0
	v_add_f32_e32 v31, v31, v42
	v_add_f32_e32 v42, v31, v43

.LBB0_141:
	v_mov_b32_e32 v18, v22
	s_nop 1
	v_permlane32_swap_b32_e32 v22, v18
	s_waitcnt lgkmcnt(0)
	v_add_f32_e32 v18, v22, v18
	v_mov_b32_e32 v19, v18
	s_nop 1
	v_permlane16_swap_b32_e32 v18, v19
	s_waitcnt lgkmcnt(0)
	v_add_f32_e32 v18, v18, v19
	s_nop 1
	v_add_f32_dpp v19, v18, v18 row_ror:8 row_mask:0xf bank_mask:0xf
	s_waitcnt lgkmcnt(0)
	v_mov_b32_e32 v18, v19
	s_nop 1
	v_add_f32_dpp v19, v18, v18 row_ror:4 row_mask:0xf bank_mask:0xf
	s_waitcnt lgkmcnt(0)
	v_mov_b32_e32 v18, v19
	s_nop 1
	v_add_f32_dpp v19, v18, v18 quad_perm:[2,3,0,1] row_mask:0xf bank_mask:0xf
	s_waitcnt lgkmcnt(0)
	v_mov_b32_e32 v18, v19
	s_nop 1
	v_add_f32_dpp v19, v18, v18 quad_perm:[1,0,3,2] row_mask:0xf bank_mask:0xf
	s_and_b64 exec, exec, s[42:43]
	s_cbranch_execz .LBB0_102
	s_waitcnt lgkmcnt(0)
	v_mov_b32_e32 v18, v19
	v_fmamk_f32 v18, v18, 0x3a800000, v229
	v_mul_f32_e32 v19, 0x4f800000, v18
	v_cmp_gt_f32_e32 vcc, s5, v18
	s_nop 1
	v_cndmask_b32_e32 v18, v18, v19, vcc
	v_sqrt_f32_e32 v19, v18
	s_nop 0
	v_add_u32_e32 v20, -1, v19
	v_fma_f32 v22, -v20, v19, v18
	v_add_u32_e32 v21, 1, v19
	v_cmp_ge_f32_e64 s[44:45], 0, v22
	s_nop 1
	v_cndmask_b32_e64 v20, v19, v20, s[44:45]
	v_fma_f32 v19, -v21, v19, v18
	v_cmp_lt_f32_e64 s[44:45], 0, v19
	s_nop 1
	v_cndmask_b32_e64 v19, v20, v21, s[44:45]
	v_mul_f32_e32 v20, 0x37800000, v19
	v_cndmask_b32_e32 v19, v19, v20, vcc
	v_cmp_class_f32_e32 vcc, v18, v230
	s_nop 1
	v_cndmask_b32_e32 v18, v19, v18, vcc
	v_div_scale_f32 v19, s[18:19], v18, v18, 1.0
	v_rcp_f32_e32 v20, v19
	s_nop 0
	v_fma_f32 v21, -v19, v20, 1.0
	v_fmac_f32_e32 v20, v21, v20
	v_div_scale_f32 v21, vcc, 1.0, v18, 1.0
	v_mul_f32_e32 v22, v21, v20
	v_fma_f32 v23, -v19, v22, v21
	v_fmac_f32_e32 v22, v23, v20
	v_fma_f32 v19, -v19, v22, v21
	v_div_fmas_f32 v19, v19, v20, v22
	v_div_fixup_f32 v20, v19, v18, 1.0
	v_lshl_add_u64 v[18:19], v[64:65], 2, s[86:87]
	global_store_dword v[18:19], v20, off
	s_branch .LBB0_102
.LBB0_143:
	s_nop 0
	s_nop 0
	s_nop 0
	s_nop 0
	s_nop 0
	s_nop 0
	s_nop 0
	s_nop 0
	s_nop 0
	s_nop 0
	s_or_b64 exec, exec, s[62:63]
	s_mov_b64 s[40:41], 0
	s_mov_b32 s20, 0xb000

.LBB0_301:
	s_or_b64 exec, exec, s[46:47]
	s_waitcnt vmcnt(4)
	v_mov_b32_e32 v70, v69
	s_nop 1
	v_permlane32_swap_b32_e32 v69, v70
	v_ashrrev_i32_e32 v19, 31, v18
	v_lshlrev_b64 v[18:19], 11, v[18:19]
	v_lshl_add_u64 v[20:21], v[52:53], 0, v[18:19]
	v_lshl_add_u64 v[22:23], v[54:55], 0, v[18:19]
	s_waitcnt lgkmcnt(0)
	v_add_f32_e32 v69, v69, v70
	v_mov_b32_e32 v70, v69
	s_nop 1
	v_permlane16_swap_b32_e32 v69, v70
	global_load_dwordx4 v[26:29], v[20:21], off
	global_load_dwordx4 v[30:33], v[22:23], off
	s_nop 0
	global_load_dwordx4 v[18:21], v[20:21], off offset:1024
	s_nop 0
	global_load_dwordx4 v[22:25], v[22:23], off offset:1024
	s_waitcnt lgkmcnt(0)
	v_add_f32_e32 v69, v69, v70
	s_nop 1
	v_add_f32_dpp v70, v69, v69 row_ror:8 row_mask:0xf bank_mask:0xf
	s_waitcnt lgkmcnt(0)
	v_mov_b32_e32 v69, v70
	s_nop 1
	v_add_f32_dpp v70, v69, v69 row_ror:4 row_mask:0xf bank_mask:0xf
	s_waitcnt lgkmcnt(0)
	v_mov_b32_e32 v69, v70
	s_nop 1
	v_add_f32_dpp v70, v69, v69 quad_perm:[2,3,0,1] row_mask:0xf bank_mask:0xf
	s_waitcnt lgkmcnt(0)
	v_mov_b32_e32 v69, v70
	s_nop 1
	v_add_f32_dpp v70, v69, v69 quad_perm:[1,0,3,2] row_mask:0xf bank_mask:0xf
	s_waitcnt lgkmcnt(0)
	v_mov_b32_e32 v69, v70
	v_fmamk_f32 v69, v69, 0x3a800000, v229
	v_cmp_gt_f32_e32 vcc, s5, v69
	v_mul_f32_e32 v70, 0x4f800000, v69
	s_nop 0
	v_cndmask_b32_e32 v69, v69, v70, vcc
	v_sqrt_f32_e32 v70, v69
	s_nop 0
	v_add_u32_e32 v71, -1, v70
	v_fma_f32 v72, -v71, v70, v69
	v_cmp_ge_f32_e64 s[46:47], 0, v72
	v_add_u32_e32 v72, 1, v70
	s_nop 0
	v_cndmask_b32_e64 v71, v70, v71, s[46:47]
	v_fma_f32 v70, -v72, v70, v69
	v_cmp_lt_f32_e64 s[46:47], 0, v70
	s_nop 1
	v_cndmask_b32_e64 v70, v71, v72, s[46:47]
	v_mul_f32_e32 v71, 0x37800000, v70
	v_cndmask_b32_e32 v70, v70, v71, vcc
	v_cmp_class_f32_e32 vcc, v69, v230
	s_nop 1
	v_cndmask_b32_e32 v69, v70, v69, vcc
	v_div_scale_f32 v70, s[16:17], v69, v69, 1.0
	v_rcp_f32_e32 v71, v70
	s_nop 0
	v_fma_f32 v72, -v70, v71, 1.0
	v_fmac_f32_e32 v71, v72, v71
	v_div_scale_f32 v72, vcc, 1.0, v69, 1.0
	v_mul_f32_e32 v73, v72, v71
	v_fma_f32 v74, -v70, v73, v72
	v_fmac_f32_e32 v73, v74, v71
	v_fma_f32 v70, -v70, v73, v72
	v_div_fmas_f32 v70, v70, v71, v73
	v_div_fixup_f32 v69, v70, v69, 1.0
	s_waitcnt vmcnt(5)
	v_lshlrev_b32_e32 v71, 16, v46
	v_lshlrev_b32_e32 v70, 16, v42
	v_mul_f32_e32 v71, v69, v71
	v_and_b32_e32 v46, 0xffff0000, v46
	v_fmac_f32_e32 v70, v6, v71
	v_and_b32_e32 v42, 0xffff0000, v42
	v_mul_f32_e32 v46, v69, v46
	v_lshlrev_b32_e32 v71, 16, v47
	v_fmac_f32_e32 v42, v7, v46
	v_lshlrev_b32_e32 v46, 16, v43
	v_mul_f32_e32 v71, v69, v71
	v_and_b32_e32 v47, 0xffff0000, v47
	v_fmac_f32_e32 v46, v8, v71
	v_and_b32_e32 v43, 0xffff0000, v43
	v_mul_f32_e32 v47, v69, v47
	v_lshlrev_b32_e32 v71, 16, v48
	v_fmac_f32_e32 v43, v9, v47
	v_lshlrev_b32_e32 v47, 16, v44
	v_mul_f32_e32 v71, v69, v71
	v_and_b32_e32 v48, 0xffff0000, v48
	v_fmac_f32_e32 v47, v14, v71
	v_and_b32_e32 v44, 0xffff0000, v44
	v_mul_f32_e32 v48, v69, v48
	v_lshlrev_b32_e32 v71, 16, v49
	v_and_b32_e32 v49, 0xffff0000, v49
	v_fmac_f32_e32 v44, v15, v48
	v_lshlrev_b32_e32 v48, 16, v45
	v_and_b32_e32 v45, 0xffff0000, v45
	v_mul_f32_e32 v49, v69, v49
	v_mul_f32_e32 v71, v69, v71
	v_fmac_f32_e32 v45, v17, v49
	v_cvt_pk_bf16_f32 v42, v70, v42
	v_fmac_f32_e32 v48, v16, v71
	v_cvt_pk_bf16_f32 v43, v46, v43
	v_cvt_pk_bf16_f32 v44, v47, v44
	v_cvt_pk_bf16_f32 v45, v48, v45
	global_store_dwordx4 v[60:61], v[42:45], off
	v_lshlrev_b32_e32 v46, 16, v42
	s_nop 0
	v_and_b32_e32 v42, 0xffff0000, v42
	v_mul_f32_e32 v42, v42, v42
	v_fmac_f32_e32 v42, v46, v46
	v_lshlrev_b32_e32 v46, 16, v43
	v_and_b32_e32 v43, 0xffff0000, v43
	v_mul_f32_e32 v43, v43, v43
	v_fmac_f32_e32 v43, v46, v46
	v_add_f32_e32 v42, v42, v43
	v_lshlrev_b32_e32 v43, 16, v44
	v_and_b32_e32 v44, 0xffff0000, v44
	v_mul_f32_e32 v44, v44, v44
	v_fmac_f32_e32 v44, v43, v43
	v_add_f32_e32 v42, v42, v44
	v_and_b32_e32 v44, 0xffff0000, v45
	v_lshlrev_b32_e32 v43, 16, v45
	v_mul_f32_e32 v44, v44, v44
	v_fmac_f32_e32 v44, v43, v43
	v_add_f32_e32 v42, v42, v44
	s_waitcnt vmcnt(5)
	v_lshlrev_b32_e32 v44, 16, v38
	v_lshlrev_b32_e32 v43, 16, v34
	v_mul_f32_e32 v44, v69, v44
	v_and_b32_e32 v38, 0xffff0000, v38
	v_fmac_f32_e32 v43, v10, v44
	v_and_b32_e32 v34, 0xffff0000, v34
	v_mul_f32_e32 v38, v69, v38
	v_lshlrev_b32_e32 v44, 16, v39
	v_fmac_f32_e32 v34, v11, v38
	v_lshlrev_b32_e32 v38, 16, v35
	v_mul_f32_e32 v44, v69, v44
	v_and_b32_e32 v39, 0xffff0000, v39
	v_fmac_f32_e32 v38, v12, v44
	v_and_b32_e32 v35, 0xffff0000, v35
	v_mul_f32_e32 v39, v69, v39
	v_lshlrev_b32_e32 v44, 16, v40
	v_fmac_f32_e32 v35, v13, v39
	v_lshlrev_b32_e32 v39, 16, v36
	v_mul_f32_e32 v44, v69, v44
	v_and_b32_e32 v40, 0xffff0000, v40
	v_fmac_f32_e32 v39, v2, v44
	v_and_b32_e32 v36, 0xffff0000, v36
	v_mul_f32_e32 v40, v69, v40
	v_lshlrev_b32_e32 v44, 16, v41
	v_and_b32_e32 v41, 0xffff0000, v41
	v_fmac_f32_e32 v36, v3, v40
	v_lshlrev_b32_e32 v40, 16, v37
	v_and_b32_e32 v37, 0xffff0000, v37
	v_mul_f32_e32 v41, v69, v41
	v_mul_f32_e32 v44, v69, v44
	v_fmac_f32_e32 v37, v5, v41
	v_cvt_pk_bf16_f32 v34, v43, v34
	v_fmac_f32_e32 v40, v4, v44
	v_cvt_pk_bf16_f32 v35, v38, v35
	v_cvt_pk_bf16_f32 v36, v39, v36
	v_cvt_pk_bf16_f32 v37, v40, v37
	global_store_dwordx4 v[60:61], v[34:37], off offset:1024
	v_lshlrev_b32_e32 v38, 16, v34
	s_nop 0
	v_and_b32_e32 v34, 0xffff0000, v34
	v_mul_f32_e32 v34, v34, v34
	v_fmac_f32_e32 v34, v38, v38
	v_lshlrev_b32_e32 v38, 16, v35
	v_and_b32_e32 v35, 0xffff0000, v35
	v_mul_f32_e32 v35, v35, v35
	v_add_f32_e32 v34, v42, v34
	v_fmac_f32_e32 v35, v38, v38
	v_add_f32_e32 v34, v34, v35
	v_lshlrev_b32_e32 v35, 16, v36
	v_and_b32_e32 v36, 0xffff0000, v36
	v_mul_f32_e32 v36, v36, v36
	v_fmac_f32_e32 v36, v35, v35
	v_add_f32_e32 v34, v34, v36
	v_and_b32_e32 v36, 0xffff0000, v37
	v_lshlrev_b32_e32 v35, 16, v37
	v_mul_f32_e32 v36, v36, v36
	v_fmac_f32_e32 v36, v35, v35
	v_add_f32_e32 v34, v34, v36
	v_mov_b32_e32 v35, v34
	s_nop 1
	v_permlane32_swap_b32_e32 v34, v35
	s_waitcnt lgkmcnt(0)
	v_add_f32_e32 v34, v34, v35
	v_mov_b32_e32 v35, v34
	s_nop 1
	v_permlane16_swap_b32_e32 v34, v35
	s_waitcnt lgkmcnt(0)
	v_add_f32_e32 v34, v34, v35
	s_nop 1
	v_add_f32_dpp v35, v34, v34 row_ror:8 row_mask:0xf bank_mask:0xf
	s_waitcnt lgkmcnt(0)
	v_mov_b32_e32 v34, v35
	s_nop 1
	v_add_f32_dpp v35, v34, v34 row_ror:4 row_mask:0xf bank_mask:0xf
	s_waitcnt lgkmcnt(0)
	v_mov_b32_e32 v34, v35
	s_nop 1
	v_add_f32_dpp v35, v34, v34 quad_perm:[2,3,0,1] row_mask:0xf bank_mask:0xf
	s_waitcnt lgkmcnt(0)
	v_mov_b32_e32 v34, v35
	s_nop 1
	v_add_f32_dpp v35, v34, v34 quad_perm:[1,0,3,2] row_mask:0xf bank_mask:0xf
	s_and_saveexec_b64 s[68:69], s[42:43]
	s_cbranch_execz .LBB0_303
	s_waitcnt lgkmcnt(0)
	v_mov_b32_e32 v34, v35
	v_fmamk_f32 v34, v34, 0x3a800000, v229
	v_mul_f32_e32 v35, 0x4f800000, v34
	v_cmp_gt_f32_e32 vcc, s5, v34
	s_nop 1
	v_cndmask_b32_e32 v34, v34, v35, vcc
	v_sqrt_f32_e32 v35, v34
	s_nop 0
	v_add_u32_e32 v36, -1, v35
	v_fma_f32 v38, -v36, v35, v34
	v_add_u32_e32 v37, 1, v35
	v_cmp_ge_f32_e64 s[46:47], 0, v38
	s_nop 1
	v_cndmask_b32_e64 v36, v35, v36, s[46:47]
	v_fma_f32 v35, -v37, v35, v34
	v_cmp_lt_f32_e64 s[46:47], 0, v35
	s_nop 1
	v_cndmask_b32_e64 v35, v36, v37, s[46:47]
	v_mul_f32_e32 v36, 0x37800000, v35
	v_cndmask_b32_e32 v35, v35, v36, vcc
	v_cmp_class_f32_e32 vcc, v34, v230
	s_nop 1
	v_cndmask_b32_e32 v34, v35, v34, vcc
	v_div_scale_f32 v35, s[16:17], v34, v34, 1.0
	v_rcp_f32_e32 v36, v35
	s_nop 0
	v_fma_f32 v37, -v35, v36, 1.0
	v_fmac_f32_e32 v36, v37, v36
	v_div_scale_f32 v37, vcc, 1.0, v34, 1.0
	v_mul_f32_e32 v38, v37, v36
	v_fma_f32 v39, -v35, v38, v37
	v_fmac_f32_e32 v38, v39, v36
	v_fma_f32 v35, -v35, v38, v37
	v_div_fmas_f32 v35, v35, v36, v38
	v_div_fixup_f32 v36, v35, v34, 1.0
	v_lshl_add_u64 v[34:35], v[58:59], 2, s[86:87]
	global_store_dword v[34:35], v36, off
.LBB0_303:
	s_or_b64 exec, exec, s[68:69]
	s_and_saveexec_b64 s[46:47], s[44:45]
	s_cbranch_execz .LBB0_284
	v_mov_b32_e32 v34, v57
	s_nop 1
	v_permlane32_swap_b32_e32 v57, v34
	s_waitcnt vmcnt(4)
	v_lshlrev_b32_e32 v37, 16, v30
	v_and_b32_e32 v30, 0xffff0000, v30
	v_lshlrev_b32_e32 v39, 16, v31
	v_and_b32_e32 v31, 0xffff0000, v31
	s_waitcnt lgkmcnt(0)
	v_add_f32_e32 v34, v57, v34
	v_mov_b32_e32 v35, v34
	s_nop 1
	v_permlane16_swap_b32_e32 v34, v35
	v_lshlrev_b32_e32 v36, 16, v26
	v_and_b32_e32 v26, 0xffff0000, v26
	v_lshlrev_b32_e32 v38, 16, v27
	v_and_b32_e32 v27, 0xffff0000, v27
	s_waitcnt lgkmcnt(0)
	v_add_f32_e32 v34, v34, v35
	s_nop 1
	v_add_f32_dpp v35, v34, v34 row_ror:8 row_mask:0xf bank_mask:0xf
	v_lshlrev_b32_e32 v41, 16, v32
	v_and_b32_e32 v32, 0xffff0000, v32
	v_lshlrev_b32_e32 v40, 16, v28
	v_and_b32_e32 v28, 0xffff0000, v28
	s_waitcnt lgkmcnt(0)
	v_mov_b32_e32 v34, v35
	s_nop 1
	v_add_f32_dpp v35, v34, v34 row_ror:4 row_mask:0xf bank_mask:0xf
	v_ashrrev_i32_e32 v57, 31, v56
	s_waitcnt lgkmcnt(0)
	v_mov_b32_e32 v34, v35
	s_nop 1
	v_add_f32_dpp v35, v34, v34 quad_perm:[2,3,0,1] row_mask:0xf bank_mask:0xf
	s_waitcnt lgkmcnt(0)
	v_mov_b32_e32 v34, v35
	s_nop 1
	v_add_f32_dpp v35, v34, v34 quad_perm:[1,0,3,2] row_mask:0xf bank_mask:0xf
	s_waitcnt lgkmcnt(0)
	v_mov_b32_e32 v34, v35
	v_fmamk_f32 v34, v34, 0x3a800000, v229
	v_mul_f32_e32 v35, 0x4f800000, v34
	v_cmp_gt_f32_e32 vcc, s5, v34
	s_nop 1
	v_cndmask_b32_e32 v34, v34, v35, vcc
	v_sqrt_f32_e32 v35, v34
	s_nop 0
	v_add_u32_e32 v42, -1, v35
	v_add_u32_e32 v43, 1, v35
	v_fma_f32 v44, -v42, v35, v34
	v_fma_f32 v45, -v43, v35, v34
	v_cmp_ge_f32_e64 s[44:45], 0, v44
	s_nop 1
	v_cndmask_b32_e64 v35, v35, v42, s[44:45]
	v_cmp_lt_f32_e64 s[44:45], 0, v45
	s_nop 1
	v_cndmask_b32_e64 v35, v35, v43, s[44:45]
	v_mul_f32_e32 v42, 0x37800000, v35
	v_cndmask_b32_e32 v35, v35, v42, vcc
	v_cmp_class_f32_e32 vcc, v34, v230
	s_nop 1
	v_cndmask_b32_e32 v34, v35, v34, vcc
	v_div_scale_f32 v35, s[16:17], v34, v34, 1.0
	v_rcp_f32_e32 v42, v35
	v_div_scale_f32 v43, vcc, 1.0, v34, 1.0
	v_fma_f32 v44, -v35, v42, 1.0
	v_fmac_f32_e32 v42, v44, v42
	v_mul_f32_e32 v44, v43, v42
	v_fma_f32 v45, -v35, v44, v43
	v_fmac_f32_e32 v44, v45, v42
	v_fma_f32 v35, -v35, v44, v43
	v_div_fmas_f32 v35, v35, v42, v44
	v_div_fixup_f32 v34, v35, v34, 1.0
	v_mul_f32_e32 v30, v34, v30
	v_mul_f32_e32 v31, v34, v31
	v_fmac_f32_e32 v26, v7, v30
	v_fmac_f32_e32 v27, v9, v31
	v_mul_f32_e32 v30, v34, v32
	v_lshlrev_b32_e32 v31, 16, v33
	v_fmac_f32_e32 v28, v15, v30
	v_lshlrev_b32_e32 v30, 16, v29
	v_mul_f32_e32 v31, v34, v31
	v_fmac_f32_e32 v30, v16, v31
	v_and_b32_e32 v31, 0xffff0000, v33
	v_mul_f32_e32 v35, v34, v37
	v_and_b32_e32 v29, 0xffff0000, v29
	v_mul_f32_e32 v31, v34, v31
	v_mul_f32_e32 v37, v34, v39
	v_fmac_f32_e32 v36, v6, v35
	v_fmac_f32_e32 v29, v17, v31
	v_cvt_pk_bf16_f32 v26, v36, v26
	v_fmac_f32_e32 v38, v8, v37
	v_and_b32_e32 v31, 0xffff0000, v26
	v_cvt_pk_bf16_f32 v27, v38, v27
	v_cvt_pk_bf16_f32 v29, v30, v29
	v_lshlrev_b32_e32 v30, 16, v26
	v_mul_f32_e32 v31, v31, v31
	v_and_b32_e32 v32, 0xffff0000, v27
	v_fmac_f32_e32 v31, v30, v30
	v_lshlrev_b32_e32 v30, 16, v27
	v_mul_f32_e32 v32, v32, v32
	v_mul_f32_e32 v39, v34, v41
	v_fmac_f32_e32 v32, v30, v30
	v_fmac_f32_e32 v40, v14, v39
	v_cvt_pk_bf16_f32 v28, v40, v28
	v_add_f32_e32 v30, v31, v32
	v_and_b32_e32 v32, 0xffff0000, v28
	v_lshlrev_b32_e32 v31, 16, v28
	v_mul_f32_e32 v32, v32, v32
	v_fmac_f32_e32 v32, v31, v31
	v_add_f32_e32 v30, v30, v32
	v_and_b32_e32 v32, 0xffff0000, v29
	v_lshlrev_b32_e32 v31, 16, v29
	v_mul_f32_e32 v32, v32, v32
	v_fmac_f32_e32 v32, v31, v31
	v_add_f32_e32 v30, v30, v32
	s_waitcnt vmcnt(2)
	v_lshlrev_b32_e32 v32, 16, v22
	v_lshlrev_b32_e32 v31, 16, v18
	v_mul_f32_e32 v32, v34, v32
	v_and_b32_e32 v22, 0xffff0000, v22
	v_fmac_f32_e32 v31, v10, v32
	v_and_b32_e32 v18, 0xffff0000, v18
	v_mul_f32_e32 v22, v34, v22
	v_lshlrev_b32_e32 v32, 16, v23
	v_fmac_f32_e32 v18, v11, v22
	v_lshlrev_b32_e32 v22, 16, v19
	v_mul_f32_e32 v32, v34, v32
	v_and_b32_e32 v23, 0xffff0000, v23
	v_fmac_f32_e32 v22, v12, v32
	v_and_b32_e32 v19, 0xffff0000, v19
	v_mul_f32_e32 v23, v34, v23
	v_lshlrev_b32_e32 v32, 16, v24
	v_fmac_f32_e32 v19, v13, v23
	v_lshlrev_b32_e32 v23, 16, v20
	v_mul_f32_e32 v32, v34, v32
	v_fmac_f32_e32 v23, v2, v32
	v_and_b32_e32 v32, 0xffff0000, v20
	v_and_b32_e32 v20, 0xffff0000, v24
	v_mul_f32_e32 v20, v34, v20
	v_fmac_f32_e32 v32, v3, v20
	v_lshlrev_b32_e32 v20, 16, v25
	v_lshlrev_b32_e32 v24, 16, v21
	v_mul_f32_e32 v20, v34, v20
	v_fmac_f32_e32 v24, v4, v20
	v_and_b32_e32 v20, 0xffff0000, v25
	v_and_b32_e32 v33, 0xffff0000, v21
	v_mul_f32_e32 v20, v34, v20
	v_fmac_f32_e32 v33, v5, v20
	v_cvt_pk_bf16_f32 v20, v31, v18
	v_cvt_pk_bf16_f32 v21, v22, v19
	v_cvt_pk_bf16_f32 v22, v23, v32
	v_cvt_pk_bf16_f32 v23, v24, v33
	s_nop 0
	v_and_b32_e32 v19, 0xffff0000, v20
	v_lshlrev_b32_e32 v18, 16, v20
	v_mul_f32_e32 v19, v19, v19
	v_fmac_f32_e32 v19, v18, v18
	v_and_b32_e32 v24, 0xffff0000, v21
	v_add_f32_e32 v18, v30, v19
	v_lshlrev_b32_e32 v19, 16, v21
	v_mul_f32_e32 v24, v24, v24
	v_fmac_f32_e32 v24, v19, v19
	v_add_f32_e32 v18, v18, v24
	v_and_b32_e32 v24, 0xffff0000, v22
	v_lshlrev_b32_e32 v19, 16, v22
	v_mul_f32_e32 v24, v24, v24
	v_fmac_f32_e32 v24, v19, v19
	v_add_f32_e32 v18, v18, v24
	v_and_b32_e32 v24, 0xffff0000, v23
	v_lshlrev_b32_e32 v19, 16, v23
	v_mul_f32_e32 v24, v24, v24
	v_fmac_f32_e32 v24, v19, v19
	v_add_f32_e32 v18, v18, v24
	v_mov_b32_e32 v19, v18
	s_nop 1
	v_permlane32_swap_b32_e32 v18, v19
	v_lshlrev_b64 v[24:25], 11, v[56:57]
	v_lshl_add_u64 v[24:25], v[52:53], 0, v[24:25]
	global_store_dwordx4 v[24:25], v[26:29], off
	global_store_dwordx4 v[24:25], v[20:23], off offset:1024
	s_waitcnt lgkmcnt(0)
	v_add_f32_e32 v18, v18, v19
	v_mov_b32_e32 v19, v18
	s_nop 1
	v_permlane16_swap_b32_e32 v18, v19
	s_waitcnt lgkmcnt(0)
	v_add_f32_e32 v18, v18, v19
	s_nop 1
	v_add_f32_dpp v19, v18, v18 row_ror:8 row_mask:0xf bank_mask:0xf
	s_waitcnt lgkmcnt(0)
	v_mov_b32_e32 v18, v19
	s_nop 1
	v_add_f32_dpp v19, v18, v18 row_ror:4 row_mask:0xf bank_mask:0xf
	s_waitcnt lgkmcnt(0)
	v_mov_b32_e32 v18, v19
	s_nop 1
	v_add_f32_dpp v19, v18, v18 quad_perm:[2,3,0,1] row_mask:0xf bank_mask:0xf
	s_waitcnt lgkmcnt(0)
	v_mov_b32_e32 v18, v19
	s_nop 1
	v_add_f32_dpp v19, v18, v18 quad_perm:[1,0,3,2] row_mask:0xf bank_mask:0xf
	s_and_b64 exec, exec, s[42:43]
	s_cbranch_execz .LBB0_284
	s_waitcnt lgkmcnt(0)
	v_mov_b32_e32 v18, v19
	v_fmamk_f32 v18, v18, 0x3a800000, v229
	v_mul_f32_e32 v19, 0x4f800000, v18
	v_cmp_gt_f32_e32 vcc, s5, v18
	s_nop 1
	v_cndmask_b32_e32 v18, v18, v19, vcc
	v_sqrt_f32_e32 v19, v18
	s_nop 0
	v_add_u32_e32 v20, -1, v19
	v_fma_f32 v22, -v20, v19, v18
	v_add_u32_e32 v21, 1, v19
	v_cmp_ge_f32_e64 s[44:45], 0, v22
	s_nop 1
	v_cndmask_b32_e64 v20, v19, v20, s[44:45]
	v_fma_f32 v19, -v21, v19, v18
	v_cmp_lt_f32_e64 s[44:45], 0, v19
	s_nop 1
	v_cndmask_b32_e64 v19, v20, v21, s[44:45]
	v_mul_f32_e32 v20, 0x37800000, v19
	v_cndmask_b32_e32 v19, v19, v20, vcc
	v_cmp_class_f32_e32 vcc, v18, v230
	s_nop 1
	v_cndmask_b32_e32 v18, v19, v18, vcc
	v_div_scale_f32 v19, s[16:17], v18, v18, 1.0
	v_rcp_f32_e32 v20, v19
	s_nop 0
	v_fma_f32 v21, -v19, v20, 1.0
	v_fmac_f32_e32 v20, v21, v20
	v_div_scale_f32 v21, vcc, 1.0, v18, 1.0
	v_mul_f32_e32 v22, v21, v20
	v_fma_f32 v23, -v19, v22, v21
	v_fmac_f32_e32 v22, v23, v20
	v_fma_f32 v19, -v19, v22, v21
	v_div_fmas_f32 v19, v19, v20, v22
	v_div_fixup_f32 v20, v19, v18, 1.0
	v_lshl_add_u64 v[18:19], v[56:57], 2, s[86:87]
	global_store_dword v[18:19], v20, off
	s_branch .LBB0_284
.LBB0_306:
	s_nop 0
	s_nop 0
	s_nop 0
	s_nop 0
	s_nop 0
	s_nop 0
	s_nop 0
	s_nop 0
	s_nop 0
	s_nop 0
	s_mov_b64 s[26:27], 0

.LBB0_669:
	s_or_b64 exec, exec, s[44:45]
	s_waitcnt vmcnt(0)
	v_cvt_pk_bf16_f32 v26, v26, v27
	v_cvt_pk_bf16_f32 v27, v28, v29
	v_cvt_pk_bf16_f32 v30, v30, v31
	v_cvt_pk_bf16_f32 v31, v32, v33
	v_cvt_pk_bf16_f32 v32, v22, v23
	v_cvt_pk_bf16_f32 v33, v24, v25
	s_nop 0
	v_and_b32_e32 v28, 0xffff0000, v26
	v_lshlrev_b32_e32 v0, 16, v26
	v_and_b32_e32 v35, 0xffff0000, v27
	v_mul_f32_e32 v28, v28, v28
	v_lshlrev_b32_e32 v29, 16, v27
	v_fmac_f32_e32 v28, v0, v0
	v_mul_f32_e32 v0, v35, v35
	v_fmac_f32_e32 v0, v29, v29
	v_add_f32_e32 v0, v28, v0
	v_cvt_pk_bf16_f32 v28, v14, v15
	v_cvt_pk_bf16_f32 v29, v16, v17
	s_nop 0
	v_and_b32_e32 v15, 0xffff0000, v28
	v_lshlrev_b32_e32 v14, 16, v28
	v_and_b32_e32 v17, 0xffff0000, v29
	v_mul_f32_e32 v15, v15, v15
	v_lshlrev_b32_e32 v16, 16, v29
	v_fmac_f32_e32 v15, v14, v14
	v_mul_f32_e32 v14, v17, v17
	v_fmac_f32_e32 v14, v16, v16
	v_add_f32_e32 v14, v15, v14
	v_and_b32_e32 v15, 0xffff0000, v30
	v_add_f32_e32 v0, v0, v14
	v_lshlrev_b32_e32 v14, 16, v30
	v_and_b32_e32 v17, 0xffff0000, v31
	v_mul_f32_e32 v15, v15, v15
	v_lshlrev_b32_e32 v16, 16, v31
	v_fmac_f32_e32 v15, v14, v14
	v_mul_f32_e32 v14, v17, v17
	v_fmac_f32_e32 v14, v16, v16
	v_add_f32_e32 v14, v15, v14
	v_and_b32_e32 v15, 0xffff0000, v32
	v_add_f32_e32 v0, v0, v14
	v_lshlrev_b32_e32 v14, 16, v32
	v_and_b32_e32 v17, 0xffff0000, v33
	v_mul_f32_e32 v15, v15, v15
	v_lshlrev_b32_e32 v16, 16, v33
	v_fmac_f32_e32 v15, v14, v14
	v_mul_f32_e32 v14, v17, v17
	v_fmac_f32_e32 v14, v16, v16
	v_add_f32_e32 v14, v15, v14
	v_add_f32_e32 v14, v0, v14
	v_and_b32_e32 v0, 64, v231
	v_add_u32_e32 v24, 64, v0
	v_xor_b32_e32 v0, 32, v231
	v_cmp_lt_i32_e32 vcc, v0, v24
	s_nop 1
	v_cndmask_b32_e32 v0, v231, v0, vcc
	v_lshlrev_b32_e32 v0, 2, v0
	v_mov_b32_e32 v15, v14
	s_nop 1
	v_permlane32_swap_b32_e32 v14, v15
	s_waitcnt lgkmcnt(0)
	v_add_f32_e32 v15, v14, v15
	v_xor_b32_e32 v14, 16, v231
	v_cmp_lt_i32_e32 vcc, v14, v24
	s_nop 1
	v_cndmask_b32_e32 v14, v231, v14, vcc
	v_lshlrev_b32_e32 v14, 2, v14
	v_mov_b32_e32 v16, v15
	s_nop 1
	v_permlane16_swap_b32_e32 v15, v16
	s_waitcnt lgkmcnt(0)
	v_add_f32_e32 v16, v15, v16
	v_xor_b32_e32 v15, 8, v231
	v_cmp_lt_i32_e32 vcc, v15, v24
	s_nop 1
	v_cndmask_b32_e32 v15, v231, v15, vcc
	v_lshlrev_b32_e32 v15, 2, v15
	s_nop 1
	v_add_f32_dpp v17, v16, v16 row_ror:8 row_mask:0xf bank_mask:0xf
	s_waitcnt lgkmcnt(0)
	v_xor_b32_e32 v16, 4, v231
	v_cmp_lt_i32_e32 vcc, v16, v24
	s_nop 1
	v_cndmask_b32_e32 v16, v231, v16, vcc
	v_lshlrev_b32_e32 v16, 2, v16
	s_nop 1
	v_add_f32_dpp v22, v17, v17 row_ror:4 row_mask:0xf bank_mask:0xf
	s_waitcnt lgkmcnt(0)
	v_mov_b32_e32 v25, v22
	v_xor_b32_e32 v17, 2, v231
	v_cmp_lt_i32_e32 vcc, v17, v24
	v_lshlrev_b64 v[22:23], 11, v[38:39]
	v_lshl_add_u64 v[42:43], v[36:37], 0, v[22:23]
	v_cndmask_b32_e32 v17, v231, v17, vcc
	v_lshlrev_b32_e32 v17, 2, v17
	s_nop 1
	v_add_f32_dpp v35, v25, v25 quad_perm:[2,3,0,1] row_mask:0xf bank_mask:0xf
	v_xor_b32_e32 v22, 1, v231
	v_cmp_lt_i32_e32 vcc, v22, v24
	global_store_dwordx2 v[42:43], v[26:27], off
	global_store_dwordx2 v[42:43], v[28:29], off offset:512
	global_store_dwordx2 v[42:43], v[30:31], off offset:1024
	global_store_dwordx2 v[42:43], v[32:33], off offset:1536
	v_cndmask_b32_e32 v22, v231, v22, vcc
	s_waitcnt lgkmcnt(0)
	v_mov_b32_e32 v23, v35
	v_lshlrev_b32_e32 v22, 2, v22
	s_nop 1
	v_add_f32_dpp v24, v23, v23 quad_perm:[1,0,3,2] row_mask:0xf bank_mask:0xf
	s_and_saveexec_b64 s[44:45], s[38:39]
	s_cbranch_execz .LBB0_671
	s_waitcnt lgkmcnt(0)
	v_mov_b32_e32 v23, v24
	v_fmamk_f32 v23, v23, 0x3a800000, v229
	v_mul_f32_e32 v24, 0x4f800000, v23
	v_cmp_gt_f32_e32 vcc, s5, v23
	s_nop 1
	v_cndmask_b32_e32 v23, v23, v24, vcc
	v_sqrt_f32_e32 v24, v23
	s_nop 0
	v_add_u32_e32 v25, -1, v24
	v_fma_f32 v27, -v25, v24, v23
	v_add_u32_e32 v26, 1, v24
	v_cmp_ge_f32_e64 s[42:43], 0, v27
	s_nop 1
	v_cndmask_b32_e64 v25, v24, v25, s[42:43]
	v_fma_f32 v24, -v26, v24, v23
	v_cmp_lt_f32_e64 s[42:43], 0, v24
	s_nop 1
	v_cndmask_b32_e64 v24, v25, v26, s[42:43]
	v_mul_f32_e32 v25, 0x37800000, v24
	v_cndmask_b32_e32 v24, v24, v25, vcc
	v_cmp_class_f32_e32 vcc, v23, v230
	s_nop 1
	v_cndmask_b32_e32 v23, v24, v23, vcc
	v_div_scale_f32 v24, s[14:15], v23, v23, 1.0
	v_rcp_f32_e32 v25, v24
	s_nop 0
	v_fma_f32 v26, -v24, v25, 1.0
	v_fmac_f32_e32 v25, v26, v25
	v_div_scale_f32 v26, vcc, 1.0, v23, 1.0
	v_mul_f32_e32 v27, v26, v25
	v_fma_f32 v28, -v24, v27, v26
	v_fmac_f32_e32 v27, v28, v25
	v_fma_f32 v24, -v24, v27, v26
	v_div_fmas_f32 v24, v24, v25, v27
	v_div_fixup_f32 v23, v24, v23, 1.0
	v_lshl_add_u64 v[24:25], v[38:39], 2, s[30:31]
	global_store_dword v[24:25], v23, off
.LBB0_671:
	s_or_b64 exec, exec, s[44:45]
	s_and_saveexec_b64 s[42:43], s[40:41]
	s_cbranch_execz .LBB0_648
	v_cvt_pk_bf16_f32 v10, v10, v11
	v_cvt_pk_bf16_f32 v11, v12, v13
	v_cvt_pk_bf16_f32 v6, v6, v7
	v_cvt_pk_bf16_f32 v7, v8, v9
	s_nop 0
	v_and_b32_e32 v13, 0xffff0000, v10
	v_lshlrev_b32_e32 v12, 16, v10
	s_waitcnt lgkmcnt(0)
	v_and_b32_e32 v24, 0xffff0000, v11
	v_mul_f32_e32 v13, v13, v13
	v_lshlrev_b32_e32 v23, 16, v11
	v_fmac_f32_e32 v13, v12, v12
	v_mul_f32_e32 v12, v24, v24
	v_fmac_f32_e32 v12, v23, v23
	v_add_f32_e32 v23, v13, v12
	v_cvt_pk_bf16_f32 v12, v2, v3
	v_cvt_pk_bf16_f32 v13, v4, v5
	v_and_b32_e32 v8, 0xffff0000, v6
	v_and_b32_e32 v3, 0xffff0000, v12
	v_lshlrev_b32_e32 v2, 16, v12
	v_and_b32_e32 v5, 0xffff0000, v13
	v_mul_f32_e32 v3, v3, v3
	v_lshlrev_b32_e32 v4, 16, v13
	v_fmac_f32_e32 v3, v2, v2
	v_mul_f32_e32 v2, v5, v5
	v_fmac_f32_e32 v2, v4, v4
	v_cvt_pk_bf16_f32 v4, v18, v19
	v_add_f32_e32 v2, v3, v2
	v_and_b32_e32 v18, 0xffff0000, v4
	v_cvt_pk_bf16_f32 v5, v20, v21
	v_lshlrev_b32_e32 v3, 16, v4
	v_and_b32_e32 v20, 0xffff0000, v5
	v_mul_f32_e32 v18, v18, v18
	v_lshlrev_b32_e32 v19, 16, v5
	v_fmac_f32_e32 v18, v3, v3
	v_mul_f32_e32 v3, v20, v20
	v_fmac_f32_e32 v3, v19, v19
	v_add_f32_e32 v2, v23, v2
	v_add_f32_e32 v3, v18, v3
	v_add_f32_e32 v2, v2, v3
	v_lshlrev_b32_e32 v3, 16, v6
	v_and_b32_e32 v18, 0xffff0000, v7
	v_mul_f32_e32 v8, v8, v8
	v_lshlrev_b32_e32 v9, 16, v7
	v_fmac_f32_e32 v8, v3, v3
	v_mul_f32_e32 v3, v18, v18
	v_fmac_f32_e32 v3, v9, v9
	v_add_f32_e32 v3, v8, v3
	v_add_f32_e32 v2, v2, v3
	v_mov_b32_e32 v0, v2
	s_nop 1
	v_permlane32_swap_b32_e32 v2, v0
	s_waitcnt lgkmcnt(0)
	v_add_f32_e32 v0, v2, v0
	v_mov_b32_e32 v2, v0
	s_nop 1
	v_permlane16_swap_b32_e32 v0, v2
	s_waitcnt lgkmcnt(0)
	v_add_f32_e32 v0, v0, v2
	s_nop 1
	v_add_f32_dpp v2, v0, v0 row_ror:8 row_mask:0xf bank_mask:0xf
	s_waitcnt lgkmcnt(0)
	v_mov_b32_e32 v0, v2
	s_nop 1
	v_add_f32_dpp v2, v0, v0 row_ror:4 row_mask:0xf bank_mask:0xf
	s_waitcnt lgkmcnt(0)
	v_mov_b32_e32 v0, v2
	s_nop 1
	v_add_f32_dpp v14, v0, v0 quad_perm:[2,3,0,1] row_mask:0xf bank_mask:0xf
	v_lshlrev_b64 v[2:3], 11, v[40:41]
	v_lshl_add_u64 v[8:9], v[36:37], 0, v[2:3]
	global_store_dwordx2 v[8:9], v[10:11], off
	global_store_dwordx2 v[8:9], v[12:13], off offset:512
	global_store_dwordx2 v[8:9], v[4:5], off offset:1024
	global_store_dwordx2 v[8:9], v[6:7], off offset:1536
	s_waitcnt lgkmcnt(0)
	v_mov_b32_e32 v0, v14
	s_nop 1
	v_add_f32_dpp v2, v0, v0 quad_perm:[1,0,3,2] row_mask:0xf bank_mask:0xf
	s_and_b64 exec, exec, s[38:39]
	s_cbranch_execz .LBB0_648
	s_waitcnt lgkmcnt(0)
	v_mov_b32_e32 v0, v2
	v_fmamk_f32 v0, v0, 0x3a800000, v229
	v_mul_f32_e32 v2, 0x4f800000, v0
	v_cmp_gt_f32_e32 vcc, s5, v0
	s_nop 1
	v_cndmask_b32_e32 v0, v0, v2, vcc
	v_sqrt_f32_e32 v2, v0
	s_nop 0
	v_add_u32_e32 v3, -1, v2
	v_fma_f32 v5, -v3, v2, v0
	v_add_u32_e32 v4, 1, v2
	v_cmp_ge_f32_e64 s[40:41], 0, v5
	s_nop 1
	v_cndmask_b32_e64 v3, v2, v3, s[40:41]
	v_fma_f32 v2, -v4, v2, v0
	v_cmp_lt_f32_e64 s[40:41], 0, v2
	s_nop 1
	v_cndmask_b32_e64 v2, v3, v4, s[40:41]
	v_mul_f32_e32 v3, 0x37800000, v2
	v_cndmask_b32_e32 v2, v2, v3, vcc
	v_cmp_class_f32_e32 vcc, v0, v230
	s_nop 1
	v_cndmask_b32_e32 v0, v2, v0, vcc
	v_div_scale_f32 v2, s[14:15], v0, v0, 1.0
	v_rcp_f32_e32 v3, v2
	s_nop 0
	v_fma_f32 v4, -v2, v3, 1.0
	v_fmac_f32_e32 v3, v4, v3
	v_div_scale_f32 v4, vcc, 1.0, v0, 1.0
	v_mul_f32_e32 v5, v4, v3
	v_fma_f32 v6, -v2, v5, v4
	v_fmac_f32_e32 v5, v6, v3
	v_fma_f32 v2, -v2, v5, v4
	v_div_fmas_f32 v2, v2, v3, v5
	v_div_fixup_f32 v0, v2, v0, 1.0
	v_lshl_add_u64 v[2:3], v[40:41], 2, s[30:31]
	global_store_dword v[2:3], v0, off
	s_branch .LBB0_648
